# v82 + p0wait: phase-0 weight-copy loop uses counted vmcnt(28) waits in steady state instead of hipcc full drain at loop top
# baseline (speedup 1.0000x reference)
.LBB0_226:
	v_lshlrev_b32_e32 v102, 3, v1
	v_add_u32_e32 v110, 0x200, v1
	v_add_u32_e32 v112, 0x400, v1
	v_add_u32_e32 v114, 0x600, v1
	v_and_b32_e32 v100, 0x7c, v101
	s_movk_i32 s4, 0x104
	v_and_b32_e32 v102, 0x78, v102
	v_ashrrev_i32_e32 v108, 4, v1
	v_ashrrev_i32_e32 v110, 4, v110
	v_ashrrev_i32_e32 v112, 4, v112
	v_ashrrev_i32_e32 v114, 4, v114
	v_lshlrev_b32_e32 v104, 1, v100
	v_mad_u32_u24 v107, v102, s4, 0
	v_lshlrev_b32_e32 v116, 1, v108
	v_lshlrev_b32_e32 v117, 1, v110
	v_lshlrev_b32_e32 v118, 1, v112
	v_lshlrev_b32_e32 v119, 1, v114
	s_add_i32 s5, 0, 0x10400
	v_add_u32_e32 v105, 0, v104
	v_add_u32_e32 v109, v107, v116
	v_add_u32_e32 v111, v107, v117
	v_add_u32_e32 v113, v107, v118
	v_add_u32_e32 v115, v107, v119
	v_add_u32_e32 v107, s5, v104
	v_mov_b32_e32 v104, s5
	v_mul_lo_u32 v106, v98, s4
	v_mad_u32_u24 v104, v102, s4, v104
	s_lshl_b32 s16, s33, 1
	s_mov_b32 s7, 0
	v_mov_b32_e32 v103, 0
	v_ashrrev_i32_e32 v99, 31, v98
	v_add_u32_e32 v116, v104, v116
	v_add_u32_e32 v117, v104, v117
	v_add_u32_e32 v118, v104, v118
	v_add_u32_e32 v119, v104, v119
	s_mul_i32 s19, s33, 5
	s_lshl_b32 s44, s33, 2
	s_mul_i32 s45, s33, 3
	v_add_u32_e32 v120, v105, v106
	v_lshlrev_b32_e32 v104, 1, v102
	v_add_u32_e32 v121, v107, v106
	s_mov_b32 s27, s21
	s_mov_b32 s47, s61
	s_mov_b32 s48, s63
	s_mov_b32 s49, s62
	s_mov_b64 s[36:37], s[28:29]
	s_waitcnt vmcnt(0)
	s_branch .Lmy_p0_top

.LBB0_228:
	s_lshl_b32 s100, s33, 2
	s_add_i32 s100, s100, s27
	s_cmpk_lt_i32 s100, 0x2230
	s_cbranch_scc1 .Lmy_p0_counted
	s_waitcnt vmcnt(0)
	s_branch .Lmy_p0_top
.Lmy_p0_counted:
	s_waitcnt vmcnt(28)
.Lmy_p0_top:
	v_mul_f32_e32 v102, v123, v2
	v_mul_f32_e32 v105, v123, v3
	v_cvt_pk_bf16_f32 v102, v102, v105
	ds_write_b32 v120, v102
	v_mul_f32_e32 v102, v123, v4
	v_mul_f32_e32 v105, v123, v5
	v_cvt_pk_bf16_f32 v102, v102, v105
	ds_write_b32 v120, v102 offset:4
	v_mul_f32_e32 v102, v124, v6
	v_mul_f32_e32 v105, v124, v7
	v_cvt_pk_bf16_f32 v102, v102, v105
	ds_write_b32 v120, v102 offset:4160
	v_mul_f32_e32 v102, v124, v8
	v_mul_f32_e32 v105, v124, v9
	v_cvt_pk_bf16_f32 v102, v102, v105
	ds_write_b32 v120, v102 offset:4164
	v_mul_f32_e32 v102, v122, v10
	v_mul_f32_e32 v105, v122, v11
	v_cvt_pk_bf16_f32 v102, v102, v105
	ds_write_b32 v120, v102 offset:8320
	v_mul_f32_e32 v102, v122, v12
	v_mul_f32_e32 v105, v122, v13
	v_cvt_pk_bf16_f32 v102, v102, v105
	ds_write_b32 v120, v102 offset:8324
	v_mul_f32_e32 v102, v125, v14
	v_mul_f32_e32 v105, v125, v15
	v_cvt_pk_bf16_f32 v102, v102, v105
	ds_write_b32 v120, v102 offset:12480
	v_mul_f32_e32 v102, v125, v16
	v_mul_f32_e32 v105, v125, v17
	v_cvt_pk_bf16_f32 v102, v102, v105
	ds_write_b32 v120, v102 offset:12484
	v_mul_f32_e32 v102, v127, v18
	v_mul_f32_e32 v105, v127, v19
	v_cvt_pk_bf16_f32 v102, v102, v105
	ds_write_b32 v120, v102 offset:16640
	v_mul_f32_e32 v102, v127, v20
	v_mul_f32_e32 v105, v127, v21
	v_cvt_pk_bf16_f32 v102, v102, v105
	ds_write_b32 v120, v102 offset:16644
	v_mul_f32_e32 v102, v128, v22
	v_mul_f32_e32 v105, v128, v23
	v_cvt_pk_bf16_f32 v102, v102, v105
	ds_write_b32 v120, v102 offset:20800
	v_mul_f32_e32 v102, v128, v24
	v_mul_f32_e32 v105, v128, v25
	v_cvt_pk_bf16_f32 v102, v102, v105
	ds_write_b32 v120, v102 offset:20804
	v_mul_f32_e32 v102, v129, v26
	v_mul_f32_e32 v105, v129, v27
	v_cvt_pk_bf16_f32 v102, v102, v105
	ds_write_b32 v120, v102 offset:24960
	v_mul_f32_e32 v102, v129, v28
	s_add_i32 s24, s27, s33
	v_mul_f32_e32 v105, v129, v29
	v_cvt_pk_bf16_f32 v102, v102, v105
	s_add_i32 s46, s24, s33
	ds_write_b32 v120, v102 offset:24964
	v_mul_f32_e32 v102, v126, v30
	s_add_i32 s46, s46, s33
	s_add_i32 s30, s45, s27
	v_mul_f32_e32 v105, v126, v31
	v_cvt_pk_bf16_f32 v102, v102, v105
	ds_write_b32 v120, v102 offset:29120
	v_mul_f32_e32 v102, v126, v32
	s_cmpk_gt_i32 s30, 0x222f
	s_mov_b32 s50, s31
	s_mov_b32 s6, s34
	v_mul_f32_e32 v105, v126, v33
	v_cvt_pk_bf16_f32 v102, v102, v105
	ds_write_b32 v120, v102 offset:29124
	s_waitcnt lgkmcnt(0)
	s_barrier
	s_cbranch_scc1 .LBB0_291
	s_cmpk_lt_i32 s30, 0x1c0
	s_cbranch_scc1 .LBB0_254
	s_cmpk_gt_u32 s30, 0x2bf
	s_mov_b64 s[4:5], -1
	s_cbranch_scc0 .LBB0_252
	s_cmpk_gt_u32 s30, 0x3bf
	s_cbranch_scc0 .LBB0_249
	s_cmpk_gt_u32 s30, 0x4bf
	s_cbranch_scc0 .LBB0_246
	s_cmpk_gt_u32 s30, 0x54f
	s_cbranch_scc0 .LBB0_243
	s_cmpk_gt_u32 s30, 0x1acf
	s_cbranch_scc0 .LBB0_240
	s_cmpk_gt_u32 s30, 0x202f
	s_cbranch_scc0 .LBB0_237
	s_add_i32 s30, s46, 0xab0
	s_mov_b64 s[4:5], 0

.LBB0_291:
	s_cmpk_lt_i32 s24, 0x2230
	s_cselect_b64 s[40:41], -1, 0
	s_lshr_b32 s4, s34, 7
	v_cvt_f32_u32_e32 v102, s4
	s_sub_i32 s34, 0, s4
	s_abs_i32 s30, s61
	s_ashr_i32 s5, s61, 31
	v_rcp_iflag_f32_e32 v102, v102
	s_nop 0
	v_mul_f32_e32 v102, 0x4f7ffffe, v102
	v_cvt_u32_f32_e32 v102, v102
	s_nop 0
	v_readfirstlane_b32 s35, v102
	s_mul_i32 s34, s34, s35
	s_mul_hi_u32 s34, s35, s34
	s_add_i32 s35, s35, s34
	s_mul_hi_u32 s34, s30, s35
	s_mul_i32 s35, s34, s4
	s_sub_i32 s30, s30, s35
	s_add_i32 s38, s34, 1
	s_sub_i32 s35, s30, s4
	s_cmp_ge_u32 s30, s4
	s_cselect_b32 s34, s38, s34
	s_cselect_b32 s30, s35, s30
	s_add_i32 s35, s34, 1
	s_cmp_ge_u32 s30, s4
	s_cselect_b32 s30, s35, s34
	s_xor_b32 s30, s30, s5
	s_sub_i32 s5, s30, s5
	s_mul_i32 s4, s5, s4
	s_sub_i32 s4, s61, s4
	s_lshl_b32 s30, s4, 1
	s_add_i32 s34, s30, 0x1ffffab
	s_cmp_lt_i32 s4, 43
	s_cselect_b32 s30, s30, s34
	s_cmp_eq_u32 s31, 0
	s_cselect_b32 s30, s4, s30
	s_lshl_b32 s30, s30, 7
	ds_read_u16 v102, v109
	ds_read_u16 v105, v109 offset:260
	ds_read_u16 v106, v109 offset:520
	ds_read_u16 v107, v109 offset:780
	ds_read_u16 v148, v109 offset:1040
	ds_read_u16 v149, v109 offset:1300
	ds_read_u16 v150, v109 offset:1560
	ds_read_u16 v151, v109 offset:1820
	s_add_i32 s34, s30, s63
	s_waitcnt lgkmcnt(6)
	v_lshl_or_b32 v146, v105, 16, v102
	v_add_u32_e32 v102, s34, v108
	s_waitcnt lgkmcnt(4)
	v_lshl_or_b32 v147, v107, 16, v106
	v_mad_u64_u32 v[106:107], s[30:31], v102, s62, 0
	v_ashrrev_i32_e32 v105, 31, v102
	v_mov_b32_e32 v102, v107
	s_lshl_b32 s4, s5, 7
	s_waitcnt lgkmcnt(2)
	v_lshl_or_b32 v148, v149, 16, v148
	s_waitcnt lgkmcnt(0)
	v_lshl_or_b32 v149, v151, 16, v150
	v_mad_u64_u32 v[150:151], s[30:31], v105, s62, v[102:103]
	s_ashr_i32 s5, s4, 31
	v_mov_b32_e32 v107, v150
	s_lshl_b64 s[4:5], s[4:5], 1
	v_lshl_add_u64 v[106:107], v[106:107], 1, s[28:29]
	v_lshl_add_u64 v[106:107], v[106:107], 0, s[4:5]
	v_mov_b32_e32 v105, v103
	v_lshl_add_u64 v[106:107], v[106:107], 0, v[104:105]
	ds_read_u16 v102, v111
	ds_read_u16 v150, v111 offset:260
	ds_read_u16 v151, v111 offset:520
	ds_read_u16 v152, v111 offset:780
	ds_read_u16 v153, v111 offset:1040
	ds_read_u16 v154, v111 offset:1300
	ds_read_u16 v155, v111 offset:1560
	ds_read_u16 v156, v111 offset:1820
	global_store_dwordx4 v[106:107], v[146:149], off
	s_cmpk_gt_i32 s24, 0x222f
	s_waitcnt lgkmcnt(6)
	v_lshl_or_b32 v146, v150, 16, v102
	v_add_u32_e32 v102, s34, v110
	v_mad_u64_u32 v[106:107], s[30:31], v102, s62, 0
	v_ashrrev_i32_e32 v150, 31, v102
	v_mov_b32_e32 v102, v107
	s_waitcnt lgkmcnt(4)
	v_lshl_or_b32 v147, v152, 16, v151
	v_mad_u64_u32 v[150:151], s[30:31], v150, s62, v[102:103]
	v_mov_b32_e32 v107, v150
	v_lshl_add_u64 v[106:107], v[106:107], 1, s[28:29]
	v_lshl_add_u64 v[106:107], v[106:107], 0, s[4:5]
	s_waitcnt lgkmcnt(2)
	v_lshl_or_b32 v148, v154, 16, v153
	s_waitcnt lgkmcnt(0)
	v_lshl_or_b32 v149, v156, 16, v155
	v_lshl_add_u64 v[106:107], v[106:107], 0, v[104:105]
	ds_read_u16 v102, v113
	ds_read_u16 v150, v113 offset:260
	ds_read_u16 v151, v113 offset:520
	ds_read_u16 v152, v113 offset:780
	ds_read_u16 v153, v113 offset:1040
	ds_read_u16 v154, v113 offset:1300
	ds_read_u16 v155, v113 offset:1560
	ds_read_u16 v156, v113 offset:1820
	global_store_dwordx4 v[106:107], v[146:149], off
	s_waitcnt lgkmcnt(6)
	s_nop 0
	v_lshl_or_b32 v146, v150, 16, v102
	v_add_u32_e32 v102, s34, v112
	v_mad_u64_u32 v[106:107], s[30:31], v102, s62, 0
	v_ashrrev_i32_e32 v150, 31, v102
	v_mov_b32_e32 v102, v107
	s_waitcnt lgkmcnt(4)
	v_lshl_or_b32 v147, v152, 16, v151
	v_mad_u64_u32 v[150:151], s[30:31], v150, s62, v[102:103]
	v_mov_b32_e32 v107, v150
	v_lshl_add_u64 v[106:107], v[106:107], 1, s[28:29]
	v_lshl_add_u64 v[106:107], v[106:107], 0, s[4:5]
	s_waitcnt lgkmcnt(2)
	v_lshl_or_b32 v148, v154, 16, v153
	s_waitcnt lgkmcnt(0)
	v_lshl_or_b32 v149, v156, 16, v155
	v_lshl_add_u64 v[106:107], v[106:107], 0, v[104:105]
	ds_read_u16 v102, v115
	ds_read_u16 v150, v115 offset:260
	ds_read_u16 v151, v115 offset:520
	ds_read_u16 v152, v115 offset:780
	ds_read_u16 v153, v115 offset:1040
	ds_read_u16 v154, v115 offset:1300
	ds_read_u16 v155, v115 offset:1560
	ds_read_u16 v156, v115 offset:1820
	global_store_dwordx4 v[106:107], v[146:149], off
	s_waitcnt lgkmcnt(6)
	s_nop 0
	v_lshl_or_b32 v146, v150, 16, v102
	v_add_u32_e32 v102, s34, v114
	v_mad_u64_u32 v[106:107], s[30:31], v102, s62, 0
	v_ashrrev_i32_e32 v150, 31, v102
	v_mov_b32_e32 v102, v107
	s_waitcnt lgkmcnt(4)
	v_lshl_or_b32 v147, v152, 16, v151
	v_mad_u64_u32 v[150:151], s[30:31], v150, s62, v[102:103]
	v_mov_b32_e32 v107, v150
	v_lshl_add_u64 v[106:107], v[106:107], 1, s[28:29]
	v_lshl_add_u64 v[106:107], v[106:107], 0, s[4:5]
	s_waitcnt lgkmcnt(2)
	v_lshl_or_b32 v148, v154, 16, v153
	s_waitcnt lgkmcnt(0)
	v_lshl_or_b32 v149, v156, 16, v155
	v_lshl_add_u64 v[106:107], v[106:107], 0, v[104:105]
	global_store_dwordx4 v[106:107], v[146:149], off
	s_cbranch_scc1 .LBB0_293
	s_waitcnt vmcnt(28)
	v_mul_f32_e32 v102, v131, v34
	v_mul_f32_e32 v105, v131, v35
	v_cvt_pk_bf16_f32 v102, v102, v105
	ds_write_b32 v120, v102 offset:33280
	v_mul_f32_e32 v102, v131, v36
	v_mul_f32_e32 v105, v131, v37
	v_cvt_pk_bf16_f32 v102, v102, v105
	ds_write_b32 v120, v102 offset:33284
	v_mul_f32_e32 v102, v132, v38
	v_mul_f32_e32 v105, v132, v39
	v_cvt_pk_bf16_f32 v102, v102, v105
	ds_write_b32 v120, v102 offset:37440
	v_mul_f32_e32 v102, v132, v40
	v_mul_f32_e32 v105, v132, v41
	v_cvt_pk_bf16_f32 v102, v102, v105
	ds_write_b32 v120, v102 offset:37444
	v_mul_f32_e32 v102, v130, v42
	v_mul_f32_e32 v105, v130, v43
	v_cvt_pk_bf16_f32 v102, v102, v105
	ds_write_b32 v120, v102 offset:41600
	v_mul_f32_e32 v102, v130, v44
	v_mul_f32_e32 v105, v130, v45
	v_cvt_pk_bf16_f32 v102, v102, v105
	ds_write_b32 v120, v102 offset:41604
	v_mul_f32_e32 v102, v133, v46
	v_mul_f32_e32 v105, v133, v47
	v_cvt_pk_bf16_f32 v102, v102, v105
	ds_write_b32 v120, v102 offset:45760
	v_mul_f32_e32 v102, v133, v48
	v_mul_f32_e32 v105, v133, v49
	v_cvt_pk_bf16_f32 v102, v102, v105
	ds_write_b32 v120, v102 offset:45764
	v_mul_f32_e32 v102, v135, v50
	v_mul_f32_e32 v105, v135, v51
	v_cvt_pk_bf16_f32 v102, v102, v105
	ds_write_b32 v120, v102 offset:49920
	v_mul_f32_e32 v102, v135, v52
	v_mul_f32_e32 v105, v135, v53
	v_cvt_pk_bf16_f32 v102, v102, v105
	ds_write_b32 v120, v102 offset:49924
	v_mul_f32_e32 v102, v136, v54
	v_mul_f32_e32 v105, v136, v55
	v_cvt_pk_bf16_f32 v102, v102, v105
	ds_write_b32 v120, v102 offset:54080
	v_mul_f32_e32 v102, v136, v56
	v_mul_f32_e32 v105, v136, v57
	v_cvt_pk_bf16_f32 v102, v102, v105
	ds_write_b32 v120, v102 offset:54084
	v_mul_f32_e32 v102, v137, v58
	v_mul_f32_e32 v105, v137, v59
	v_cvt_pk_bf16_f32 v102, v102, v105
	ds_write_b32 v120, v102 offset:58240
	v_mul_f32_e32 v102, v137, v60
	v_mul_f32_e32 v105, v137, v61
	v_cvt_pk_bf16_f32 v102, v102, v105
	ds_write_b32 v120, v102 offset:58244
	v_mul_f32_e32 v102, v134, v62
	v_mul_f32_e32 v105, v134, v63
	v_cvt_pk_bf16_f32 v102, v102, v105
	ds_write_b32 v120, v102 offset:62400
	v_mul_f32_e32 v102, v134, v64
	v_mul_f32_e32 v105, v134, v65
	v_cvt_pk_bf16_f32 v102, v102, v105
	ds_write_b32 v120, v102 offset:62404

.LBB0_342:
	s_add_i32 s4, s16, s27
	s_cmpk_lt_i32 s4, 0x2230
	s_cselect_b64 s[22:23], -1, 0
	s_cmpk_gt_i32 s4, 0x222f
	s_cbranch_scc1 .LBB0_344
	s_waitcnt vmcnt(28)
	v_mul_f32_e32 v102, v139, v66
	v_mul_f32_e32 v105, v139, v67
	v_cvt_pk_bf16_f32 v102, v102, v105
	ds_write_b32 v121, v102
	v_mul_f32_e32 v102, v139, v68
	v_mul_f32_e32 v105, v139, v69
	v_cvt_pk_bf16_f32 v102, v102, v105
	ds_write_b32 v121, v102 offset:4
	v_mul_f32_e32 v102, v140, v70
	v_mul_f32_e32 v105, v140, v71
	v_cvt_pk_bf16_f32 v102, v102, v105
	ds_write_b32 v121, v102 offset:4160
	v_mul_f32_e32 v102, v140, v72
	v_mul_f32_e32 v105, v140, v73
	v_cvt_pk_bf16_f32 v102, v102, v105
	ds_write_b32 v121, v102 offset:4164
	v_mul_f32_e32 v102, v138, v74
	v_mul_f32_e32 v105, v138, v75
	v_cvt_pk_bf16_f32 v102, v102, v105
	ds_write_b32 v121, v102 offset:8320
	v_mul_f32_e32 v102, v138, v76
	v_mul_f32_e32 v105, v138, v77
	v_cvt_pk_bf16_f32 v102, v102, v105
	ds_write_b32 v121, v102 offset:8324
	v_mul_f32_e32 v102, v141, v78
	v_mul_f32_e32 v105, v141, v79
	v_cvt_pk_bf16_f32 v102, v102, v105
	ds_write_b32 v121, v102 offset:12480
	v_mul_f32_e32 v102, v141, v80
	v_mul_f32_e32 v105, v141, v81
	v_cvt_pk_bf16_f32 v102, v102, v105
	ds_write_b32 v121, v102 offset:12484
	v_mul_f32_e32 v102, v143, v82
	v_mul_f32_e32 v105, v143, v83
	v_cvt_pk_bf16_f32 v102, v102, v105
	ds_write_b32 v121, v102 offset:16640
	v_mul_f32_e32 v102, v143, v84
	v_mul_f32_e32 v105, v143, v85
	v_cvt_pk_bf16_f32 v102, v102, v105
	ds_write_b32 v121, v102 offset:16644
	v_mul_f32_e32 v102, v144, v86
	v_mul_f32_e32 v105, v144, v87
	v_cvt_pk_bf16_f32 v102, v102, v105
	ds_write_b32 v121, v102 offset:20800
	v_mul_f32_e32 v102, v144, v88
	v_mul_f32_e32 v105, v144, v89
	v_cvt_pk_bf16_f32 v102, v102, v105
	ds_write_b32 v121, v102 offset:20804
	v_mul_f32_e32 v102, v145, v90
	v_mul_f32_e32 v105, v145, v91
	v_cvt_pk_bf16_f32 v102, v102, v105
	ds_write_b32 v121, v102 offset:24960
	v_mul_f32_e32 v102, v145, v92
	v_mul_f32_e32 v105, v145, v93
	v_cvt_pk_bf16_f32 v102, v102, v105
	ds_write_b32 v121, v102 offset:24964
	v_mul_f32_e32 v102, v142, v94
	v_mul_f32_e32 v105, v142, v95
	v_cvt_pk_bf16_f32 v102, v102, v105
	ds_write_b32 v121, v102 offset:29120
	v_mul_f32_e32 v102, v142, v96
	v_mul_f32_e32 v105, v142, v97
	v_cvt_pk_bf16_f32 v102, v102, v105
	ds_write_b32 v121, v102 offset:29124
